# P0 weight-copy stores made write-through (sc1) so the grid sync after P0 has less dirty L2 to write back
# baseline (speedup 1.0000x reference)
.Lp0w_nozero:
	s_mov_b64 s[20:21], exec
	v_cmp_gt_u32_e32 vcc, s17, v3
	s_and_b64 exec, exec, vcc
	global_load_dwordx4 v[20:23], v19, s[18:19] nt
	s_add_u32 s18, s18, s15
	s_addc_u32 s19, s19, 0
	global_load_dwordx4 v[24:27], v19, s[18:19] nt
	s_add_u32 s18, s18, s15
	s_addc_u32 s19, s19, 0
	global_load_dwordx4 v[28:31], v19, s[18:19] nt
	s_add_u32 s18, s18, s15
	s_addc_u32 s19, s19, 0
	global_load_dwordx4 v[32:35], v19, s[18:19] nt
	s_add_u32 s18, s18, s15
	s_addc_u32 s19, s19, 0
	global_load_dwordx4 v[36:39], v19, s[18:19] nt
	s_add_u32 s18, s18, s15
	s_addc_u32 s19, s19, 0
	global_load_dwordx4 v[40:43], v19, s[18:19] nt
	s_add_u32 s18, s18, s15
	s_addc_u32 s19, s19, 0
	global_load_dwordx4 v[44:47], v19, s[18:19] nt
	s_add_u32 s18, s18, s15
	s_addc_u32 s19, s19, 0
	global_load_dwordx4 v[48:51], v19, s[18:19] nt
	s_add_u32 s18, s18, s15
	s_addc_u32 s19, s19, 0
	global_load_dwordx4 v[52:55], v19, s[18:19] nt
	s_add_u32 s18, s18, s15
	s_addc_u32 s19, s19, 0
	global_load_dwordx4 v[56:59], v19, s[18:19] nt
	s_add_u32 s18, s18, s15
	s_addc_u32 s19, s19, 0
	global_load_dwordx4 v[60:63], v19, s[18:19] nt
	s_add_u32 s18, s18, s15
	s_addc_u32 s19, s19, 0
	global_load_dwordx4 v[64:67], v19, s[18:19] nt
	s_add_u32 s18, s18, s15
	s_addc_u32 s19, s19, 0
	global_load_dwordx4 v[68:71], v19, s[18:19] nt
	s_add_u32 s18, s18, s15
	s_addc_u32 s19, s19, 0
	global_load_dwordx4 v[76:79], v19, s[18:19] nt
	s_add_u32 s18, s18, s15
	s_addc_u32 s19, s19, 0
	global_load_dwordx4 v[80:83], v19, s[18:19] nt
	s_add_u32 s18, s18, s15
	s_addc_u32 s19, s19, 0
	global_load_dwordx4 v[84:87], v19, s[18:19] nt
	s_add_u32 s18, s18, s15
	s_addc_u32 s19, s19, 0
	global_load_dwordx4 v[88:91], v19, s[18:19] nt
	s_add_u32 s18, s18, s15
	s_addc_u32 s19, s19, 0
	global_load_dwordx4 v[92:95], v19, s[18:19] nt
	s_add_u32 s18, s18, s15
	s_addc_u32 s19, s19, 0
	global_load_dwordx4 v[108:111], v19, s[18:19] nt
	s_add_u32 s18, s18, s15
	s_addc_u32 s19, s19, 0
	global_load_dwordx4 v[112:115], v19, s[18:19] nt
	s_add_u32 s18, s18, s15
	s_addc_u32 s19, s19, 0
	global_load_dwordx4 v[116:119], v19, s[18:19] nt
	s_add_u32 s18, s18, s15
	s_addc_u32 s19, s19, 0
	global_load_dwordx4 v[120:123], v19, s[18:19] nt
	s_add_u32 s18, s18, s15
	s_addc_u32 s19, s19, 0
	global_load_dwordx4 v[124:127], v19, s[18:19] nt
	s_add_u32 s18, s18, s15
	s_addc_u32 s19, s19, 0
	global_load_dwordx4 v[128:131], v19, s[18:19] nt
	s_add_u32 s18, s18, s15
	s_addc_u32 s19, s19, 0
	global_load_dwordx4 v[132:135], v19, s[18:19] nt
	s_add_u32 s18, s18, s15
	s_addc_u32 s19, s19, 0
	global_load_dwordx4 v[136:139], v19, s[18:19] nt
	s_add_u32 s18, s18, s15
	s_addc_u32 s19, s19, 0
	global_load_dwordx4 v[140:143], v19, s[18:19] nt
	s_add_u32 s18, s18, s15
	s_addc_u32 s19, s19, 0
	global_load_dwordx4 v[144:147], v19, s[18:19] nt
	s_add_u32 s18, s18, s15
	s_addc_u32 s19, s19, 0
	global_load_dwordx4 v[148:151], v19, s[18:19] nt
	s_add_u32 s18, s18, s15
	s_addc_u32 s19, s19, 0
	global_load_dwordx4 v[152:155], v19, s[18:19] nt
	s_add_u32 s18, s18, s15
	s_addc_u32 s19, s19, 0
	global_load_dwordx4 v[156:159], v19, s[18:19] nt
	s_add_u32 s18, s18, s15
	s_addc_u32 s19, s19, 0
	global_load_dwordx4 v[160:163], v19, s[18:19] nt
	s_mov_b64 exec, s[20:21]
	s_lshl_b32 s14, s5, 18
	s_lshl_b32 s22, s4, 7
	s_add_i32 s14, s14, s22
	s_add_u32 s22, s12, s14
	s_addc_u32 s23, s13, 0
	s_waitcnt vmcnt(0)
	v_cvt_pk_bf16_f32 v20, v20, v24
	v_cvt_pk_bf16_f32 v21, v21, v25
	v_cvt_pk_bf16_f32 v22, v22, v26
	v_cvt_pk_bf16_f32 v23, v23, v27
	v_cvt_pk_bf16_f32 v28, v28, v32
	v_cvt_pk_bf16_f32 v29, v29, v33
	v_cvt_pk_bf16_f32 v30, v30, v34
	v_cvt_pk_bf16_f32 v31, v31, v35
	v_cvt_pk_bf16_f32 v36, v36, v40
	v_cvt_pk_bf16_f32 v37, v37, v41
	v_cvt_pk_bf16_f32 v38, v38, v42
	v_cvt_pk_bf16_f32 v39, v39, v43
	v_cvt_pk_bf16_f32 v44, v44, v48
	v_cvt_pk_bf16_f32 v45, v45, v49
	v_cvt_pk_bf16_f32 v46, v46, v50
	v_cvt_pk_bf16_f32 v47, v47, v51
	v_cvt_pk_bf16_f32 v52, v52, v56
	v_cvt_pk_bf16_f32 v53, v53, v57
	v_cvt_pk_bf16_f32 v54, v54, v58
	v_cvt_pk_bf16_f32 v55, v55, v59
	v_cvt_pk_bf16_f32 v60, v60, v64
	v_cvt_pk_bf16_f32 v61, v61, v65
	v_cvt_pk_bf16_f32 v62, v62, v66
	v_cvt_pk_bf16_f32 v63, v63, v67
	v_cvt_pk_bf16_f32 v68, v68, v76
	v_cvt_pk_bf16_f32 v69, v69, v77
	v_cvt_pk_bf16_f32 v70, v70, v78
	v_cvt_pk_bf16_f32 v71, v71, v79
	v_cvt_pk_bf16_f32 v80, v80, v84
	v_cvt_pk_bf16_f32 v81, v81, v85
	v_cvt_pk_bf16_f32 v82, v82, v86
	v_cvt_pk_bf16_f32 v83, v83, v87
	v_cvt_pk_bf16_f32 v88, v88, v92
	v_cvt_pk_bf16_f32 v89, v89, v93
	v_cvt_pk_bf16_f32 v90, v90, v94
	v_cvt_pk_bf16_f32 v91, v91, v95
	v_cvt_pk_bf16_f32 v108, v108, v112
	v_cvt_pk_bf16_f32 v109, v109, v113
	v_cvt_pk_bf16_f32 v110, v110, v114
	v_cvt_pk_bf16_f32 v111, v111, v115
	v_cvt_pk_bf16_f32 v116, v116, v120
	v_cvt_pk_bf16_f32 v117, v117, v121
	v_cvt_pk_bf16_f32 v118, v118, v122
	v_cvt_pk_bf16_f32 v119, v119, v123
	v_cvt_pk_bf16_f32 v124, v124, v128
	v_cvt_pk_bf16_f32 v125, v125, v129
	v_cvt_pk_bf16_f32 v126, v126, v130
	v_cvt_pk_bf16_f32 v127, v127, v131
	v_cvt_pk_bf16_f32 v132, v132, v136
	v_cvt_pk_bf16_f32 v133, v133, v137
	v_cvt_pk_bf16_f32 v134, v134, v138
	v_cvt_pk_bf16_f32 v135, v135, v139
	v_cvt_pk_bf16_f32 v140, v140, v144
	v_cvt_pk_bf16_f32 v141, v141, v145
	v_cvt_pk_bf16_f32 v142, v142, v146
	v_cvt_pk_bf16_f32 v143, v143, v147
	v_cvt_pk_bf16_f32 v148, v148, v152
	v_cvt_pk_bf16_f32 v149, v149, v153
	v_cvt_pk_bf16_f32 v150, v150, v154
	v_cvt_pk_bf16_f32 v151, v151, v155
	v_cvt_pk_bf16_f32 v156, v156, v160
	v_cvt_pk_bf16_f32 v157, v157, v161
	v_cvt_pk_bf16_f32 v158, v158, v162
	v_cvt_pk_bf16_f32 v159, v159, v163
	ds_write_b32 v7, v20
	ds_write_b32 v7, v21 offset:128
	ds_write_b32 v7, v22 offset:256
	ds_write_b32 v7, v23 offset:384
	ds_write_b32 v7, v28 offset:4
	ds_write_b32 v7, v29 offset:132
	ds_write_b32 v7, v30 offset:260
	ds_write_b32 v7, v31 offset:388
	ds_write_b32 v7, v36 offset:8
	ds_write_b32 v7, v37 offset:136
	ds_write_b32 v7, v38 offset:264
	ds_write_b32 v7, v39 offset:392
	ds_write_b32 v7, v44 offset:12
	ds_write_b32 v7, v45 offset:140
	ds_write_b32 v7, v46 offset:268
	ds_write_b32 v7, v47 offset:396
	ds_write_b32 v8, v52
	ds_write_b32 v8, v53 offset:128
	ds_write_b32 v8, v54 offset:256
	ds_write_b32 v8, v55 offset:384
	ds_write_b32 v8, v60 offset:4
	ds_write_b32 v8, v61 offset:132
	ds_write_b32 v8, v62 offset:260
	ds_write_b32 v8, v63 offset:388
	ds_write_b32 v8, v68 offset:8
	ds_write_b32 v8, v69 offset:136
	ds_write_b32 v8, v70 offset:264
	ds_write_b32 v8, v71 offset:392
	ds_write_b32 v8, v80 offset:12
	ds_write_b32 v8, v81 offset:140
	ds_write_b32 v8, v82 offset:268
	ds_write_b32 v8, v83 offset:396
	ds_write_b32 v9, v88
	ds_write_b32 v9, v89 offset:128
	ds_write_b32 v9, v90 offset:256
	ds_write_b32 v9, v91 offset:384
	ds_write_b32 v9, v108 offset:4
	ds_write_b32 v9, v109 offset:132
	ds_write_b32 v9, v110 offset:260
	ds_write_b32 v9, v111 offset:388
	ds_write_b32 v9, v116 offset:8
	ds_write_b32 v9, v117 offset:136
	ds_write_b32 v9, v118 offset:264
	ds_write_b32 v9, v119 offset:392
	ds_write_b32 v9, v124 offset:12
	ds_write_b32 v9, v125 offset:140
	ds_write_b32 v9, v126 offset:268
	ds_write_b32 v9, v127 offset:396
	ds_write_b32 v10, v132
	ds_write_b32 v10, v133 offset:128
	ds_write_b32 v10, v134 offset:256
	ds_write_b32 v10, v135 offset:384
	ds_write_b32 v10, v140 offset:4
	ds_write_b32 v10, v141 offset:132
	ds_write_b32 v10, v142 offset:260
	ds_write_b32 v10, v143 offset:388
	ds_write_b32 v10, v148 offset:8
	ds_write_b32 v10, v149 offset:136
	ds_write_b32 v10, v150 offset:264
	ds_write_b32 v10, v151 offset:392
	ds_write_b32 v10, v156 offset:12
	ds_write_b32 v10, v157 offset:140
	ds_write_b32 v10, v158 offset:268
	ds_write_b32 v10, v159 offset:396
	s_waitcnt lgkmcnt(0)
	ds_read_b128 v[24:27], v13
	ds_read_b128 v[32:35], v14 offset:1024
	ds_read_b128 v[40:43], v15 offset:2048
	ds_read_b128 v[48:51], v16 offset:3072
	ds_read_b128 v[56:59], v13 offset:4096
	ds_read_b128 v[64:67], v14 offset:5120
	ds_read_b128 v[76:79], v15 offset:6144
	ds_read_b128 v[84:87], v16 offset:7168
	ds_read_b128 v[92:95], v13 offset:8192
	ds_read_b128 v[112:115], v14 offset:9216
	ds_read_b128 v[120:123], v15 offset:10240
	ds_read_b128 v[128:131], v16 offset:11264
	ds_read_b128 v[136:139], v13 offset:12288
	ds_read_b128 v[144:147], v14 offset:13312
	ds_read_b128 v[152:155], v15 offset:14336
	ds_read_b128 v[160:163], v16 offset:15360
	s_waitcnt lgkmcnt(15)
	global_store_dwordx4 v17, v[24:27], s[22:23] sc1
	s_add_u32 s22, s22, 0x4000
	s_addc_u32 s23, s23, 0
	s_waitcnt lgkmcnt(14)
	global_store_dwordx4 v17, v[32:35], s[22:23] sc1
	s_add_u32 s22, s22, 0x4000
	s_addc_u32 s23, s23, 0
	s_waitcnt lgkmcnt(13)
	global_store_dwordx4 v17, v[40:43], s[22:23] sc1
	s_add_u32 s22, s22, 0x4000
	s_addc_u32 s23, s23, 0
	s_waitcnt lgkmcnt(12)
	global_store_dwordx4 v17, v[48:51], s[22:23] sc1
	s_add_u32 s22, s22, 0x4000
	s_addc_u32 s23, s23, 0
	s_waitcnt lgkmcnt(11)
	global_store_dwordx4 v17, v[56:59], s[22:23] sc1
	s_add_u32 s22, s22, 0x4000
	s_addc_u32 s23, s23, 0
	s_waitcnt lgkmcnt(10)
	global_store_dwordx4 v17, v[64:67], s[22:23] sc1
	s_add_u32 s22, s22, 0x4000
	s_addc_u32 s23, s23, 0
	s_waitcnt lgkmcnt(9)
	global_store_dwordx4 v17, v[76:79], s[22:23] sc1
	s_add_u32 s22, s22, 0x4000
	s_addc_u32 s23, s23, 0
	s_waitcnt lgkmcnt(8)
	global_store_dwordx4 v17, v[84:87], s[22:23] sc1
	s_add_u32 s22, s22, 0x4000
	s_addc_u32 s23, s23, 0
	s_waitcnt lgkmcnt(7)
	global_store_dwordx4 v17, v[92:95], s[22:23] sc1
	s_add_u32 s22, s22, 0x4000
	s_addc_u32 s23, s23, 0
	s_waitcnt lgkmcnt(6)
	global_store_dwordx4 v17, v[112:115], s[22:23] sc1
	s_add_u32 s22, s22, 0x4000
	s_addc_u32 s23, s23, 0
	s_waitcnt lgkmcnt(5)
	global_store_dwordx4 v17, v[120:123], s[22:23] sc1
	s_add_u32 s22, s22, 0x4000
	s_addc_u32 s23, s23, 0
	s_waitcnt lgkmcnt(4)
	global_store_dwordx4 v17, v[128:131], s[22:23] sc1
	s_add_u32 s22, s22, 0x4000
	s_addc_u32 s23, s23, 0
	s_waitcnt lgkmcnt(3)
	global_store_dwordx4 v17, v[136:139], s[22:23] sc1
	s_add_u32 s22, s22, 0x4000
	s_addc_u32 s23, s23, 0
	s_waitcnt lgkmcnt(2)
	global_store_dwordx4 v17, v[144:147], s[22:23] sc1
	s_add_u32 s22, s22, 0x4000
	s_addc_u32 s23, s23, 0
	s_waitcnt lgkmcnt(1)
	global_store_dwordx4 v17, v[152:155], s[22:23] sc1
	s_add_u32 s22, s22, 0x4000
	s_addc_u32 s23, s23, 0
	s_waitcnt lgkmcnt(0)
	global_store_dwordx4 v17, v[160:163], s[22:23] sc1
	s_addk_i32 s1, 0x380
	s_add_i32 s3, s3, 1
	s_cmp_lt_u32 s3, 2
	s_cbranch_scc1 .Lp0w_round
